# GEMM1 K-loop: per-phase s_setprio flips removed, one static s_setprio 1 for waves 0-3 before the tile loop (reset at phase exit)
# speedup vs baseline: 1.0080x; 1.0080x over previous
.LBB0_160:
	s_add_u32 s20, s70, 0x2a484000
	s_addc_u32 s21, s71, 0
	s_and_b32 s45, s1, 3
	s_lshl_b32 s1, s0, 13
	s_lshl_b32 s3, s45, 12
	s_add_u32 s4, s88, 0x8000
	s_addc_u32 s5, s89, 0
	s_add_i32 m0, s17, 0x18000
	s_waitcnt vmcnt(0)
	v_lshl_add_u64 v[8:9], s[4:5], 0, v[130:131]
	s_waitcnt vmcnt(4)
	s_barrier
	global_load_lds_dwordx4 v[8:9], off
	v_lshl_add_u64 v[8:9], s[4:5], 0, v[134:135]
	s_add_i32 m0, s17, 0x1a000
	s_mov_b64 s[22:23], 0x80
	s_add_i32 s82, s17, 0x8000
	s_add_i32 s83, s17, 0xa000
	global_load_lds_dwordx4 v[8:9], off
	v_lshl_add_u64 v[2:3], v[2:3], 0, s[22:23]
	s_mov_b32 m0, s82
	s_add_u32 s4, s88, 0xc000
	global_load_lds_dwordx4 v[2:3], off
	v_lshl_add_u64 v[0:1], v[0:1], 0, s[22:23]
	s_mov_b32 m0, s83
	s_addc_u32 s5, s89, 0
	global_load_lds_dwordx4 v[0:1], off
	s_add_i32 m0, s17, 0x1c000
	v_lshl_add_u64 v[0:1], s[4:5], 0, v[130:131]
	global_load_lds_dwordx4 v[0:1], off
	v_lshl_add_u64 v[0:1], s[4:5], 0, v[134:135]
	s_add_i32 m0, s17, 0x1e000
	v_and_b32_e32 v8, 32, v174
	global_load_lds_dwordx4 v[0:1], off
	v_bfe_u32 v1, v191, 4, 2
	v_and_b32_e32 v0, 15, v191
	v_lshlrev_b32_e32 v3, 4, v1
	v_lshl_or_b32 v138, s0, 6, v0
	v_lshl_or_b32 v0, v0, 6, v3
	v_bitop3_b32 v9, v0, s1, v8 bitop3:0xde
	v_lshlrev_b32_e32 v0, 6, v191
	s_movk_i32 s0, 0x3c0
	v_lshlrev_b32_e32 v2, 3, v1
	v_and_or_b32 v0, v0, s0, v3
	v_bitop3_b32 v175, s3, v0, v8 bitop3:0xf6
	v_lshl_or_b32 v0, s45, 5, v2
	v_lshlrev_b32_e32 v2, 1, v0
	v_mov_b32_e32 v3, v136
	v_lshl_add_u64 v[2:3], s[70:71], 0, v[2:3]
	s_mov_b64 s[0:1], 0x1e484000
	v_cmp_eq_u32_e64 s[4:5], 0, v1
	v_lshlrev_b32_e32 v1, 10, v191
	v_lshl_add_u64 v[146:147], v[2:3], 0, s[0:1]
	v_and_b32_e32 v1, 0xe0000, v1
	v_lshlrev_b32_e32 v2, 13, v6
	s_add_u32 s10, s70, 0x1a484000
	v_or3_b32 v1, v4, v1, v2
	s_addc_u32 s11, s71, 0
	v_add_u32_e32 v156, v1, v5
	v_lshlrev_b32_e32 v1, 6, v7
	s_waitcnt vmcnt(6)
	s_add_u32 s24, s70, 0x16484000
	v_and_b32_e32 v1, 0x1e0000, v1
	s_addc_u32 s25, s71, 0
	v_mov_b32_e32 v139, v136
	v_or_b32_e32 v140, 16, v138
	v_mov_b32_e32 v141, v136
	v_or_b32_e32 v142, 32, v138
	v_mov_b32_e32 v143, v136
	v_or_b32_e32 v144, 48, v138
	v_mov_b32_e32 v145, v136
	v_or3_b32 v1, v4, v1, v2
	s_add_i32 s81, 0, 0x10000
	s_add_i32 s3, 0, 0x14000
	v_lshlrev_b32_e32 v164, 1, v0
	v_mbcnt_lo_u32_b32 v0, -1, 0
	v_lshlrev_b64 v[148:149], 8, v[138:139]
	v_lshlrev_b64 v[150:151], 8, v[140:141]
	v_lshlrev_b64 v[152:153], 8, v[142:143]
	v_lshlrev_b64 v[154:155], 8, v[144:145]
	s_ashr_i32 s78, s80, 31
	s_ashr_i32 s79, s2, 31
	v_mov_b32_e32 v157, v136
	v_add_u32_e32 v158, v1, v5
	v_mov_b32_e32 v159, v136
	v_mov_b64_e32 v[160:161], 0xa00
	v_mov_b64_e32 v[162:163], 0x9ff
	v_add_u32_e32 v139, s81, v175
	v_add_u32_e32 v141, 0, v9
	s_mov_b32 s26, 0x3e6d3388
	s_mov_b32 s28, 0x3f07dc22
	s_mov_b32 s30, 0xbf3a00e3
	s_mov_b32 s34, 0x3f35f0e3
	s_mov_b32 s38, 0xbe11a98e
	s_mov_b32 s44, 0x3e027906
	s_mov_b32 s54, 0xbf38aa3b
	v_add_u32_e32 v143, s3, v175
	v_mbcnt_hi_u32_b32 v145, -1, v0
	s_mov_b32 s0, 0
	s_barrier
	s_cmpk_gt_u32 s27, 0xff
	s_cbranch_scc1 .Lg1_noprio
	s_setprio 1
.Lg1_noprio:
	s_branch .LBB0_163

.LBB0_166:
	ds_read_b128 v[166:169], v139
	ds_read_b128 v[170:173], v139 offset:1024
	ds_read_b128 v[176:179], v139 offset:2048
	ds_read_b128 v[180:183], v139 offset:3072
	s_add_u32 s90, s88, 0xfff00080
	s_addc_u32 s91, s89, -1
	s_cmp_eq_u32 s95, 60
	s_cselect_b32 s93, s1, s91
	s_cselect_b32 s92, s18, s90
	s_cselect_b32 s91, s57, s94
	s_cselect_b32 s90, s63, s87
	v_lshl_add_u64 v[188:189], s[88:89], 0, v[156:157]
	s_add_i32 m0, s17, 0xc000
	ds_read_b128 v[184:187], v141
	ds_read_b128 v[192:195], v141 offset:1024
	ds_read_b128 v[196:199], v141 offset:2048
	ds_read_b128 v[200:203], v141 offset:3072
	ds_read_b128 v[204:207], v141 offset:4096
	ds_read_b128 v[212:215], v141 offset:5120
	ds_read_b128 v[216:219], v141 offset:6144
	ds_read_b128 v[220:223], v141 offset:7168
	global_load_lds_dwordx4 v[188:189], off
	v_lshl_add_u64 v[188:189], s[88:89], 0, v[158:159]
	s_add_i32 m0, s17, 0xe000
	s_nop 0
	global_load_lds_dwordx4 v[188:189], off
	s_waitcnt lgkmcnt(8)
	s_barrier
	s_waitcnt lgkmcnt(0)
	s_waitcnt lgkmcnt(0)
	v_mfma_f32_16x16x32_bf16 v[124:127], v[166:169], v[184:187], v[124:127]
	v_mfma_f32_16x16x32_bf16 v[116:119], v[176:179], v[184:187], v[116:119]
	v_mfma_f32_16x16x32_bf16 v[108:111], v[166:169], v[196:199], v[108:111]
	v_mfma_f32_16x16x32_bf16 v[100:103], v[176:179], v[196:199], v[100:103]
	v_mfma_f32_16x16x32_bf16 v[92:95], v[166:169], v[204:207], v[92:95]
	v_mfma_f32_16x16x32_bf16 v[84:87], v[176:179], v[204:207], v[84:87]
	v_mfma_f32_16x16x32_bf16 v[76:79], v[166:169], v[216:219], v[76:79]
	v_mfma_f32_16x16x32_bf16 v[68:71], v[176:179], v[216:219], v[68:71]
	v_mfma_f32_16x16x32_bf16 v[124:127], v[170:173], v[192:195], v[124:127]
	v_mfma_f32_16x16x32_bf16 v[116:119], v[180:183], v[192:195], v[116:119]
	v_mfma_f32_16x16x32_bf16 v[108:111], v[170:173], v[200:203], v[108:111]
	v_mfma_f32_16x16x32_bf16 v[100:103], v[180:183], v[200:203], v[100:103]
	v_mfma_f32_16x16x32_bf16 v[92:95], v[170:173], v[212:215], v[92:95]
	v_mfma_f32_16x16x32_bf16 v[84:87], v[180:183], v[212:215], v[84:87]
	v_mfma_f32_16x16x32_bf16 v[76:79], v[170:173], v[220:223], v[76:79]
	v_mfma_f32_16x16x32_bf16 v[68:71], v[180:183], v[220:223], v[68:71]
	s_barrier
	s_add_i32 vcc_lo, s81, s73
	v_lshl_add_u64 v[188:189], s[90:91], 0, v[130:131]
	s_mov_b32 m0, vcc_lo
	ds_read_b128 v[224:227], v143
	ds_read_b128 v[228:231], v143 offset:1024
	ds_read_b128 v[232:235], v143 offset:2048
	ds_read_b128 v[236:239], v143 offset:3072
	global_load_lds_dwordx4 v[188:189], off
	v_lshl_add_u64 v[188:189], s[90:91], 0, v[134:135]
	s_add_i32 m0, vcc_lo, 0x2000
	s_nop 0
	global_load_lds_dwordx4 v[188:189], off
	s_barrier
	s_waitcnt lgkmcnt(0)
	s_waitcnt lgkmcnt(0)
	v_mfma_f32_16x16x32_bf16 v[112:115], v[224:227], v[184:187], v[112:115]
	v_mfma_f32_16x16x32_bf16 v[120:123], v[232:235], v[184:187], v[120:123]
	v_mfma_f32_16x16x32_bf16 v[96:99], v[224:227], v[196:199], v[96:99]
	v_mfma_f32_16x16x32_bf16 v[104:107], v[232:235], v[196:199], v[104:107]
	v_mfma_f32_16x16x32_bf16 v[80:83], v[224:227], v[204:207], v[80:83]
	v_mfma_f32_16x16x32_bf16 v[88:91], v[232:235], v[204:207], v[88:91]
	v_mfma_f32_16x16x32_bf16 v[64:67], v[224:227], v[216:219], v[64:67]
	v_mfma_f32_16x16x32_bf16 v[72:75], v[232:235], v[216:219], v[72:75]
	v_mfma_f32_16x16x32_bf16 v[112:115], v[228:231], v[192:195], v[112:115]
	v_mfma_f32_16x16x32_bf16 v[120:123], v[236:239], v[192:195], v[120:123]
	v_mfma_f32_16x16x32_bf16 v[96:99], v[228:231], v[200:203], v[96:99]
	v_mfma_f32_16x16x32_bf16 v[104:107], v[236:239], v[200:203], v[104:107]
	v_mfma_f32_16x16x32_bf16 v[80:83], v[228:231], v[212:215], v[80:83]
	v_mfma_f32_16x16x32_bf16 v[88:91], v[236:239], v[212:215], v[88:91]
	v_mfma_f32_16x16x32_bf16 v[64:67], v[228:231], v[220:223], v[64:67]
	v_mfma_f32_16x16x32_bf16 v[72:75], v[236:239], v[220:223], v[72:75]
	s_mov_b32 m0, s17
	v_lshl_add_u64 v[188:189], s[92:93], 0, v[128:129]
	s_barrier
	ds_read_b128 v[184:187], v141 offset:16384
	ds_read_b128 v[192:195], v141 offset:17408
	ds_read_b128 v[196:199], v141 offset:18432
	ds_read_b128 v[200:203], v141 offset:19456
	ds_read_b128 v[204:207], v141 offset:20480
	ds_read_b128 v[212:215], v141 offset:21504
	ds_read_b128 v[216:219], v141 offset:22528
	ds_read_b128 v[220:223], v141 offset:23552
	global_load_lds_dwordx4 v[188:189], off
	v_lshl_add_u64 v[208:209], s[92:93], 0, v[132:133]
	s_mov_b32 m0, s75
	s_nop 0
	global_load_lds_dwordx4 v[208:209], off
	s_barrier
	s_waitcnt lgkmcnt(0)
	s_waitcnt lgkmcnt(0)
	v_mfma_f32_16x16x32_bf16 v[60:63], v[166:169], v[184:187], v[60:63]
	v_mfma_f32_16x16x32_bf16 v[52:55], v[176:179], v[184:187], v[52:55]
	v_mfma_f32_16x16x32_bf16 v[44:47], v[166:169], v[196:199], v[44:47]
	v_mfma_f32_16x16x32_bf16 v[36:39], v[176:179], v[196:199], v[36:39]
	v_mfma_f32_16x16x32_bf16 v[28:31], v[166:169], v[204:207], v[28:31]
	v_mfma_f32_16x16x32_bf16 v[20:23], v[176:179], v[204:207], v[20:23]
	v_mfma_f32_16x16x32_bf16 v[12:15], v[166:169], v[216:219], v[12:15]
	v_mfma_f32_16x16x32_bf16 v[4:7], v[176:179], v[216:219], v[4:7]
	v_mfma_f32_16x16x32_bf16 v[60:63], v[170:173], v[192:195], v[60:63]
	v_mfma_f32_16x16x32_bf16 v[52:55], v[180:183], v[192:195], v[52:55]
	v_mfma_f32_16x16x32_bf16 v[44:47], v[170:173], v[200:203], v[44:47]
	v_mfma_f32_16x16x32_bf16 v[36:39], v[180:183], v[200:203], v[36:39]
	v_mfma_f32_16x16x32_bf16 v[28:31], v[170:173], v[212:215], v[28:31]
	v_mfma_f32_16x16x32_bf16 v[20:23], v[180:183], v[212:215], v[20:23]
	v_mfma_f32_16x16x32_bf16 v[12:15], v[170:173], v[220:223], v[12:15]
	v_mfma_f32_16x16x32_bf16 v[4:7], v[180:183], v[220:223], v[4:7]
	s_barrier
	s_add_u32 vcc_lo, s90, 0x4000
	s_addc_u32 vcc_hi, s91, 0
	s_add_i32 s96, s3, s73
	v_lshl_add_u64 v[166:167], vcc, 0, v[130:131]
	s_mov_b32 m0, s96
	s_nop 0
	global_load_lds_dwordx4 v[166:167], off
	v_lshl_add_u64 v[166:167], vcc, 0, v[134:135]
	s_add_i32 m0, s96, 0x2000
	s_nop 0
	global_load_lds_dwordx4 v[166:167], off
	s_waitcnt vmcnt(6)
	s_barrier
	v_mfma_f32_16x16x32_bf16 v[48:51], v[224:227], v[184:187], v[48:51]
	v_mfma_f32_16x16x32_bf16 v[56:59], v[232:235], v[184:187], v[56:59]
	v_mfma_f32_16x16x32_bf16 v[32:35], v[224:227], v[196:199], v[32:35]
	v_mfma_f32_16x16x32_bf16 v[40:43], v[232:235], v[196:199], v[40:43]
	v_mfma_f32_16x16x32_bf16 v[16:19], v[224:227], v[204:207], v[16:19]
	v_mfma_f32_16x16x32_bf16 v[24:27], v[232:235], v[204:207], v[24:27]
	v_mfma_f32_16x16x32_bf16 v[0:3], v[224:227], v[216:219], v[0:3]
	v_mfma_f32_16x16x32_bf16 v[8:11], v[232:235], v[216:219], v[8:11]
	v_mfma_f32_16x16x32_bf16 v[48:51], v[228:231], v[192:195], v[48:51]
	v_mfma_f32_16x16x32_bf16 v[56:59], v[236:239], v[192:195], v[56:59]
	v_mfma_f32_16x16x32_bf16 v[32:35], v[228:231], v[200:203], v[32:35]
	v_mfma_f32_16x16x32_bf16 v[40:43], v[236:239], v[200:203], v[40:43]
	v_mfma_f32_16x16x32_bf16 v[16:19], v[228:231], v[212:215], v[16:19]
	v_mfma_f32_16x16x32_bf16 v[24:27], v[236:239], v[212:215], v[24:27]
	v_mfma_f32_16x16x32_bf16 v[0:3], v[228:231], v[220:223], v[0:3]
	v_mfma_f32_16x16x32_bf16 v[8:11], v[236:239], v[220:223], v[8:11]
	s_add_i32 s96, 0, 0x18000
	v_add_u32_e32 v137, s96, v175
	s_barrier
	ds_read_b128 v[166:169], v137
	ds_read_b128 v[170:173], v137 offset:1024
	ds_read_b128 v[176:179], v137 offset:2048
	ds_read_b128 v[180:183], v137 offset:3072
	s_add_u32 s92, s92, 0x100000
	s_addc_u32 s93, s93, 0
	s_mov_b32 m0, s97
	v_lshl_add_u64 v[224:225], s[92:93], 0, v[128:129]
	ds_read_b128 v[184:187], v141 offset:32768
	ds_read_b128 v[192:195], v141 offset:33792
	ds_read_b128 v[196:199], v141 offset:34816
	ds_read_b128 v[200:203], v141 offset:35840
	ds_read_b128 v[204:207], v141 offset:36864
	ds_read_b128 v[212:215], v141 offset:37888
	ds_read_b128 v[216:219], v141 offset:38912
	ds_read_b128 v[220:223], v141 offset:39936
	global_load_lds_dwordx4 v[224:225], off
	v_lshl_add_u64 v[224:225], s[92:93], 0, v[132:133]
	s_mov_b32 m0, s55
	s_nop 0
	global_load_lds_dwordx4 v[224:225], off
	s_waitcnt lgkmcnt(8)
	s_barrier
	s_waitcnt lgkmcnt(0)
	s_waitcnt lgkmcnt(0)
	v_mfma_f32_16x16x32_bf16 v[124:127], v[166:169], v[184:187], v[124:127]
	v_mfma_f32_16x16x32_bf16 v[116:119], v[176:179], v[184:187], v[116:119]
	v_mfma_f32_16x16x32_bf16 v[108:111], v[166:169], v[196:199], v[108:111]
	v_mfma_f32_16x16x32_bf16 v[100:103], v[176:179], v[196:199], v[100:103]
	v_mfma_f32_16x16x32_bf16 v[92:95], v[166:169], v[204:207], v[92:95]
	v_mfma_f32_16x16x32_bf16 v[84:87], v[176:179], v[204:207], v[84:87]
	v_mfma_f32_16x16x32_bf16 v[76:79], v[166:169], v[216:219], v[76:79]
	v_mfma_f32_16x16x32_bf16 v[68:71], v[176:179], v[216:219], v[68:71]
	v_mfma_f32_16x16x32_bf16 v[124:127], v[170:173], v[192:195], v[124:127]
	v_mfma_f32_16x16x32_bf16 v[116:119], v[180:183], v[192:195], v[116:119]
	v_mfma_f32_16x16x32_bf16 v[108:111], v[170:173], v[200:203], v[108:111]
	v_mfma_f32_16x16x32_bf16 v[100:103], v[180:183], v[200:203], v[100:103]
	v_mfma_f32_16x16x32_bf16 v[92:95], v[170:173], v[212:215], v[92:95]
	v_mfma_f32_16x16x32_bf16 v[84:87], v[180:183], v[212:215], v[84:87]
	v_mfma_f32_16x16x32_bf16 v[76:79], v[170:173], v[220:223], v[76:79]
	v_mfma_f32_16x16x32_bf16 v[68:71], v[180:183], v[220:223], v[68:71]
	s_barrier
	s_add_i32 vcc_lo, 0, 0x1c000
	s_add_u32 s92, s90, 0x8000
	s_addc_u32 s93, s91, 0
	s_add_i32 s96, s96, s73
	v_add_u32_e32 v137, vcc_lo, v175
	v_lshl_add_u64 v[240:241], s[92:93], 0, v[130:131]
	s_mov_b32 m0, s96
	ds_read_b128 v[224:227], v137
	ds_read_b128 v[228:231], v137 offset:1024
	ds_read_b128 v[232:235], v137 offset:2048
	ds_read_b128 v[236:239], v137 offset:3072
	global_load_lds_dwordx4 v[240:241], off
	v_lshl_add_u64 v[240:241], s[92:93], 0, v[134:135]
	s_add_i32 m0, s96, 0x2000
	s_nop 0
	global_load_lds_dwordx4 v[240:241], off
	s_barrier
	s_waitcnt lgkmcnt(0)
	s_waitcnt lgkmcnt(0)
	v_mfma_f32_16x16x32_bf16 v[112:115], v[224:227], v[184:187], v[112:115]
	v_mfma_f32_16x16x32_bf16 v[120:123], v[232:235], v[184:187], v[120:123]
	v_mfma_f32_16x16x32_bf16 v[96:99], v[224:227], v[196:199], v[96:99]
	v_mfma_f32_16x16x32_bf16 v[104:107], v[232:235], v[196:199], v[104:107]
	v_mfma_f32_16x16x32_bf16 v[80:83], v[224:227], v[204:207], v[80:83]
	v_mfma_f32_16x16x32_bf16 v[88:91], v[232:235], v[204:207], v[88:91]
	v_mfma_f32_16x16x32_bf16 v[64:67], v[224:227], v[216:219], v[64:67]
	v_mfma_f32_16x16x32_bf16 v[72:75], v[232:235], v[216:219], v[72:75]
	v_mfma_f32_16x16x32_bf16 v[112:115], v[228:231], v[192:195], v[112:115]
	v_mfma_f32_16x16x32_bf16 v[120:123], v[236:239], v[192:195], v[120:123]
	v_mfma_f32_16x16x32_bf16 v[96:99], v[228:231], v[200:203], v[96:99]
	v_mfma_f32_16x16x32_bf16 v[104:107], v[236:239], v[200:203], v[104:107]
	v_mfma_f32_16x16x32_bf16 v[80:83], v[228:231], v[212:215], v[80:83]
	v_mfma_f32_16x16x32_bf16 v[88:91], v[236:239], v[212:215], v[88:91]
	v_mfma_f32_16x16x32_bf16 v[64:67], v[228:231], v[220:223], v[64:67]
	v_mfma_f32_16x16x32_bf16 v[72:75], v[236:239], v[220:223], v[72:75]
	s_mov_b32 m0, s82
	v_lshl_add_u64 v[188:189], v[188:189], 0, s[22:23]
	s_barrier
	ds_read_b128 v[184:187], v141 offset:49152
	ds_read_b128 v[192:195], v141 offset:50176
	ds_read_b128 v[196:199], v141 offset:51200
	ds_read_b128 v[200:203], v141 offset:52224
	ds_read_b128 v[204:207], v141 offset:53248
	ds_read_b128 v[212:215], v141 offset:54272
	ds_read_b128 v[216:219], v141 offset:55296
	ds_read_b128 v[220:223], v141 offset:56320
	global_load_lds_dwordx4 v[188:189], off
	v_lshl_add_u64 v[188:189], v[208:209], 0, s[22:23]
	s_mov_b32 m0, s83
	s_nop 0
	global_load_lds_dwordx4 v[188:189], off
	s_barrier
	s_waitcnt lgkmcnt(0)
	s_waitcnt lgkmcnt(0)
	v_mfma_f32_16x16x32_bf16 v[60:63], v[166:169], v[184:187], v[60:63]
	v_mfma_f32_16x16x32_bf16 v[52:55], v[176:179], v[184:187], v[52:55]
	v_mfma_f32_16x16x32_bf16 v[44:47], v[166:169], v[196:199], v[44:47]
	v_mfma_f32_16x16x32_bf16 v[36:39], v[176:179], v[196:199], v[36:39]
	v_mfma_f32_16x16x32_bf16 v[28:31], v[166:169], v[204:207], v[28:31]
	v_mfma_f32_16x16x32_bf16 v[20:23], v[176:179], v[204:207], v[20:23]
	v_mfma_f32_16x16x32_bf16 v[12:15], v[166:169], v[216:219], v[12:15]
	v_mfma_f32_16x16x32_bf16 v[4:7], v[176:179], v[216:219], v[4:7]
	v_mfma_f32_16x16x32_bf16 v[60:63], v[170:173], v[192:195], v[60:63]
	v_mfma_f32_16x16x32_bf16 v[52:55], v[180:183], v[192:195], v[52:55]
	v_mfma_f32_16x16x32_bf16 v[44:47], v[170:173], v[200:203], v[44:47]
	v_mfma_f32_16x16x32_bf16 v[36:39], v[180:183], v[200:203], v[36:39]
	v_mfma_f32_16x16x32_bf16 v[28:31], v[170:173], v[212:215], v[28:31]
	v_mfma_f32_16x16x32_bf16 v[20:23], v[180:183], v[212:215], v[20:23]
	v_mfma_f32_16x16x32_bf16 v[12:15], v[170:173], v[220:223], v[12:15]
	v_mfma_f32_16x16x32_bf16 v[4:7], v[180:183], v[220:223], v[4:7]
	s_barrier
	s_add_u32 s90, s90, 0xc000
	s_addc_u32 s91, s91, 0
	s_add_i32 s92, vcc_lo, s73
	v_lshl_add_u64 v[166:167], s[90:91], 0, v[130:131]
	s_mov_b32 m0, s92
	s_nop 0
	global_load_lds_dwordx4 v[166:167], off
	v_lshl_add_u64 v[166:167], s[90:91], 0, v[134:135]
	s_add_i32 m0, s92, 0x2000
	s_nop 0
	global_load_lds_dwordx4 v[166:167], off
	s_waitcnt vmcnt(6)
	s_barrier
	v_mfma_f32_16x16x32_bf16 v[48:51], v[224:227], v[184:187], v[48:51]
	v_mfma_f32_16x16x32_bf16 v[56:59], v[232:235], v[184:187], v[56:59]
	v_mfma_f32_16x16x32_bf16 v[32:35], v[224:227], v[196:199], v[32:35]
	v_mfma_f32_16x16x32_bf16 v[40:43], v[232:235], v[196:199], v[40:43]
	v_mfma_f32_16x16x32_bf16 v[16:19], v[224:227], v[204:207], v[16:19]
	v_mfma_f32_16x16x32_bf16 v[24:27], v[232:235], v[204:207], v[24:27]
	v_mfma_f32_16x16x32_bf16 v[0:3], v[224:227], v[216:219], v[0:3]
	v_mfma_f32_16x16x32_bf16 v[8:11], v[232:235], v[216:219], v[8:11]
	v_mfma_f32_16x16x32_bf16 v[48:51], v[228:231], v[192:195], v[48:51]
	v_mfma_f32_16x16x32_bf16 v[56:59], v[236:239], v[192:195], v[56:59]
	v_mfma_f32_16x16x32_bf16 v[32:35], v[228:231], v[200:203], v[32:35]
	v_mfma_f32_16x16x32_bf16 v[40:43], v[236:239], v[200:203], v[40:43]
	v_mfma_f32_16x16x32_bf16 v[16:19], v[228:231], v[212:215], v[16:19]
	v_mfma_f32_16x16x32_bf16 v[24:27], v[236:239], v[212:215], v[24:27]
	v_mfma_f32_16x16x32_bf16 v[0:3], v[228:231], v[220:223], v[0:3]
	v_mfma_f32_16x16x32_bf16 v[8:11], v[236:239], v[220:223], v[8:11]
	s_add_i32 s95, s95, 2
	s_add_u32 s87, s87, 0x10000
	s_addc_u32 s94, s94, 0
	s_add_u32 s88, s88, 0x100
	s_addc_u32 s89, s89, 0
	s_cmp_gt_u32 s95, 61
	s_barrier
	s_cbranch_scc0 .LBB0_166
	s_cmpk_gt_u32 s27, 0xff
	s_cbranch_scc1 .Lg1_nopre
	s_barrier

.LBB0_195:
	s_setprio 0
	s_waitcnt vmcnt(0)
	v_readlane_b32 s82, v242, 14
	v_readlane_b32 s54, v242, 4
	s_cmpk_gt_u32 s27, 0xff
	v_readlane_b32 s83, v242, 15
	v_readlane_b32 s81, v242, 10
	v_readlane_b32 s78, v242, 9
	v_readlane_b32 s79, v242, 8
	v_readlane_b32 s38, v242, 7
	v_readlane_b32 s44, v242, 6
	v_readlane_b32 s55, v242, 5
	s_cbranch_scc1 .LBB0_197
	s_barrier
